# add-on row-norm reduction: xor-32 step via v_permlane32_swap instead of an LDS bpermute round trip
# speedup vs baseline: 1.0007x; 1.0007x over previous
; __device__ __forceinline__ unsigned cvt_pk_bf16(float lo, float hi) { const f32x2_t v = {lo, hi}; const bf16x2_t r = __builtin_convertvector(v, bf16x2_t); return __builtin_bit_cast(unsigned, r); }
; __device__ __forceinline__ void p0_proc4(bf16_t* XB, int m0, int NGW, int lane, const f32x4 (&v)[4][4]) {
;     float s[4];
; #pragma unroll
;     for (int u = 0; u < 4; ++u) { float t = 0.f;
; #pragma unroll
;         for (int j = 0; j < 4; ++j) t += (v[u][j][0] * v[u][j][0] + v[u][j][1] * v[u][j][1]) + (v[u][j][2] * v[u][j][2] + v[u][j][3] * v[u][j][3]);
;         s[u] = t; }
; #pragma unroll
;     for (int o = 1; o < 64; o <<= 1) {
; #pragma unroll
;         for (int u = 0; u < 4; ++u) s[u] += __shfl_xor(s[u], o); }
; #pragma unroll
;     for (int u = 0; u < 4; ++u) { const int m = m0 + u * NGW; if (m >= T) break;
;         const float rstd = 1.0f / sqrtf(s[u] * (1.0f / 1024.0f) + NORM_EPS);
;         u32x2* o8 = (u32x2*)(XB + (size_t)m * 1024) + lane;
; #pragma unroll
;         for (int j = 0; j < 4; ++j) { u32x2 w; w.x = cvt_pk_bf16(v[u][j][0] * rstd, v[u][j][1] * rstd); w.y = cvt_pk_bf16(v[u][j][2] * rstd, v[u][j][3] * rstd); o8[64 * j] = w; } }
; }
.LBB0_208:
	s_cmp_eq_u32 s98, -1
	s_cbranch_scc1 .Lax_done
	s_waitcnt vmcnt(16)
	v_mul_f32_e32 v203, v232, v232
	v_mul_f32_e32 v204, v234, v234
	v_fmac_f32_e32 v203, v233, v233
	v_fmac_f32_e32 v204, v235, v235
	v_add_f32_e32 v203, v203, v204
	v_mov_b32_e32 v201, v203
	v_mul_f32_e32 v203, v236, v236
	v_mul_f32_e32 v204, v238, v238
	v_fmac_f32_e32 v203, v237, v237
	v_fmac_f32_e32 v204, v239, v239
	v_add_f32_e32 v203, v203, v204
	v_add_f32_e32 v201, v201, v203
	v_mul_f32_e32 v203, v240, v240
	v_mul_f32_e32 v204, v242, v242
	v_fmac_f32_e32 v203, v241, v241
	v_fmac_f32_e32 v204, v243, v243
	v_add_f32_e32 v203, v203, v204
	v_add_f32_e32 v201, v201, v203
	v_mul_f32_e32 v203, v244, v244
	v_mul_f32_e32 v204, v246, v246
	v_fmac_f32_e32 v203, v245, v245
	v_fmac_f32_e32 v204, v247, v247
	v_add_f32_e32 v203, v203, v204
	v_add_f32_e32 v201, v201, v203
	v_mul_f32_e32 v205, v182, v182
	v_mul_f32_e32 v206, v184, v184
	v_fmac_f32_e32 v205, v183, v183
	v_fmac_f32_e32 v206, v185, v185
	v_add_f32_e32 v205, v205, v206
	v_mov_b32_e32 v202, v205
	v_mul_f32_e32 v205, v250, v250
	v_mul_f32_e32 v206, v252, v252
	v_fmac_f32_e32 v205, v251, v251
	v_fmac_f32_e32 v206, v253, v253
	v_add_f32_e32 v205, v205, v206
	v_add_f32_e32 v202, v202, v205
	v_mul_f32_e32 v205, v178, v178
	v_mul_f32_e32 v206, v180, v180
	v_fmac_f32_e32 v205, v179, v179
	v_fmac_f32_e32 v206, v181, v181
	v_add_f32_e32 v205, v205, v206
	v_add_f32_e32 v202, v202, v205
	v_mul_f32_e32 v205, v154, v154
	v_mul_f32_e32 v206, v156, v156
	v_fmac_f32_e32 v205, v155, v155
	v_fmac_f32_e32 v206, v157, v157
	v_add_f32_e32 v205, v205, v206
	v_add_f32_e32 v202, v202, v205
	v_lshrrev_b32_e32 v210, 2, v254
	s_nop 0
	v_add_f32_dpp v201, v201, v201 quad_perm:[1,0,3,2] row_mask:0xf bank_mask:0xf
	v_add_f32_dpp v202, v202, v202 quad_perm:[1,0,3,2] row_mask:0xf bank_mask:0xf
	s_nop 0
	v_add_f32_dpp v201, v201, v201 quad_perm:[2,3,0,1] row_mask:0xf bank_mask:0xf
	v_add_f32_dpp v202, v202, v202 quad_perm:[2,3,0,1] row_mask:0xf bank_mask:0xf
	s_nop 0
	v_add_f32_dpp v201, v201, v201 row_half_mirror row_mask:0xf bank_mask:0xf
	v_add_f32_dpp v202, v202, v202 row_half_mirror row_mask:0xf bank_mask:0xf
	s_nop 0
	v_add_f32_dpp v201, v201, v201 row_mirror row_mask:0xf bank_mask:0xf
	v_add_f32_dpp v202, v202, v202 row_mirror row_mask:0xf bank_mask:0xf
	v_xor_b32_e32 v211, 64, v210
	ds_bpermute_b32 v207, v211, v201
	ds_bpermute_b32 v208, v211, v202
	s_waitcnt lgkmcnt(0)
	v_add_f32_e32 v201, v201, v207
	v_add_f32_e32 v202, v202, v208
	v_mov_b32_e32 v207, v201
	v_mov_b32_e32 v208, v202
	s_nop 1
	v_permlane32_swap_b32 v207, v201
	v_permlane32_swap_b32 v208, v202
	s_nop 1
	v_add_f32_e32 v201, v201, v207
	v_add_f32_e32 v202, v202, v208
	v_mov_b32_e32 v212, 0x358637bd
	s_nop 0
	v_fmamk_f32 v213, v201, 0x3a800000, v212
	v_fmamk_f32 v214, v202, 0x3a800000, v212
	v_rsq_f32_e32 v215, v213
	v_rsq_f32_e32 v216, v214
	s_nop 0
	v_mul_f32_e32 v217, v213, v215
	v_mul_f32_e32 v218, v214, v216
	v_fma_f32 v217, -v217, v215, 1.0
	v_fma_f32 v218, -v218, v216, 1.0
	v_mul_f32_e32 v219, 0.5, v215
	v_mul_f32_e32 v220, 0.5, v216
	v_fma_f32 v222, v219, v217, v215
	v_fma_f32 v224, v220, v218, v216
	s_lshl_b32 s100, s98, 11
	s_add_u32 s100, s100, s64
	s_addc_u32 s101, s65, 0
	s_add_u32 s100, s100, 0x1100000
	s_addc_u32 s101, s101, 0
	v_lshrrev_b32_e32 v221, 1, v254
	s_cmp_eq_u32 s32, 1
	s_cbranch_scc0 .Lax_wt
	v_pk_mul_f32 v[226:227], v[232:233], v[222:223] op_sel_hi:[1,0]
	v_pk_mul_f32 v[228:229], v[234:235], v[222:223] op_sel_hi:[1,0]
	v_cvt_pk_bf16_f32 v230, v226, v227
	v_cvt_pk_bf16_f32 v231, v228, v229
	global_store_dwordx2 v221, v[230:231], s[100:101] offset:0
	v_pk_mul_f32 v[226:227], v[236:237], v[222:223] op_sel_hi:[1,0]
	v_pk_mul_f32 v[228:229], v[238:239], v[222:223] op_sel_hi:[1,0]
	v_cvt_pk_bf16_f32 v202, v226, v227
	v_cvt_pk_bf16_f32 v203, v228, v229
	global_store_dwordx2 v221, v[202:203], s[100:101] offset:512
	v_pk_mul_f32 v[226:227], v[240:241], v[222:223] op_sel_hi:[1,0]
	v_pk_mul_f32 v[228:229], v[242:243], v[222:223] op_sel_hi:[1,0]
	v_cvt_pk_bf16_f32 v230, v226, v227
	v_cvt_pk_bf16_f32 v231, v228, v229
	global_store_dwordx2 v221, v[230:231], s[100:101] offset:1024
	v_pk_mul_f32 v[226:227], v[244:245], v[222:223] op_sel_hi:[1,0]
	v_pk_mul_f32 v[228:229], v[246:247], v[222:223] op_sel_hi:[1,0]
	v_cvt_pk_bf16_f32 v202, v226, v227
	v_cvt_pk_bf16_f32 v203, v228, v229
	global_store_dwordx2 v221, v[202:203], s[100:101] offset:1536
	v_pk_mul_f32 v[226:227], v[182:183], v[224:225] op_sel_hi:[1,0]
	v_pk_mul_f32 v[228:229], v[184:185], v[224:225] op_sel_hi:[1,0]
	v_cvt_pk_bf16_f32 v230, v226, v227
	v_cvt_pk_bf16_f32 v231, v228, v229
	global_store_dwordx2 v221, v[230:231], s[100:101] offset:2048
	v_pk_mul_f32 v[226:227], v[250:251], v[224:225] op_sel_hi:[1,0]
	v_pk_mul_f32 v[228:229], v[252:253], v[224:225] op_sel_hi:[1,0]
	v_cvt_pk_bf16_f32 v202, v226, v227
	v_cvt_pk_bf16_f32 v203, v228, v229
	global_store_dwordx2 v221, v[202:203], s[100:101] offset:2560
	v_pk_mul_f32 v[226:227], v[178:179], v[224:225] op_sel_hi:[1,0]
	v_pk_mul_f32 v[228:229], v[180:181], v[224:225] op_sel_hi:[1,0]
	v_cvt_pk_bf16_f32 v230, v226, v227
	v_cvt_pk_bf16_f32 v231, v228, v229
	global_store_dwordx2 v221, v[230:231], s[100:101] offset:3072
	v_pk_mul_f32 v[226:227], v[154:155], v[224:225] op_sel_hi:[1,0]
	v_pk_mul_f32 v[228:229], v[156:157], v[224:225] op_sel_hi:[1,0]
	v_cvt_pk_bf16_f32 v202, v226, v227
	v_cvt_pk_bf16_f32 v203, v228, v229
	global_store_dwordx2 v221, v[202:203], s[100:101] offset:3584
	s_branch .Lax_stdone
